# Wout epilogue too: counted waits at the first consumer of each residual load instead of one vmcnt(0)
# speedup vs baseline: 1.0108x; 1.0020x over previous
;     __device__ __forceinline__ void operator()(const f32x4 (&acc)[2][2][4][2], const pg8::Unit& u, int wr, int wc, int fr, int fq) const {
;         u32x4 xr[2][4][2];
; #pragma unroll
;         for (int ai = 0; ai < 2; ++ai)
; #pragma unroll
;             for (int m = 0; m < 4; ++m)
; #pragma unroll
;                 for (int bj = 0; bj < 2; ++bj)
;                     xr[ai][m][bj] = *(const u32x4*)(xb + (size_t)(u.pm * 256 + ai * 128 + wr * 64 + m * 16 + fr) * DM + u.pn * 256 + 128 * bj + 32 * wc + 8 * fq);
;         __builtin_amdgcn_sched_barrier(0);
; #pragma unroll
;         for (int ai = 0; ai < 2; ++ai)
; #pragma unroll
;             for (int m = 0; m < 4; ++m) {
;                 const int row = u.pm * 256 + ai * 128 + wr * 64 + m * 16 + fr;
;                 float ss = 0.f;
; #pragma unroll
;                 for (int bj = 0; bj < 2; ++bj) {
;                     const size_t off = (size_t)row * DM + u.pn * 256 + 128 * bj + 32 * wc + 8 * fq;
;                     const u32x4 w = xr[ai][m][bj];
;                     float y[8];
;                     y[0] = __uint_as_float(w.x << 16) + acc[ai][bj][m][0].x; y[1] = __uint_as_float(w.x & 0xffff0000u) + acc[ai][bj][m][0].y;
;                     y[2] = __uint_as_float(w.y << 16) + acc[ai][bj][m][0].z; y[3] = __uint_as_float(w.y & 0xffff0000u) + acc[ai][bj][m][0].w;
;                     y[4] = __uint_as_float(w.z << 16) + acc[ai][bj][m][1].x; y[5] = __uint_as_float(w.z & 0xffff0000u) + acc[ai][bj][m][1].y;
;                     y[6] = __uint_as_float(w.w << 16) + acc[ai][bj][m][1].z; y[7] = __uint_as_float(w.w & 0xffff0000u) + acc[ai][bj][m][1].w;
;                     store8(x2b + off, y);
; #pragma unroll
;                     for (int i = 0; i < 8; ++i) ss += y[i] * y[i];
;                 }
;                 ss += __shfl_xor(ss, 16); ss += __shfl_xor(ss, 32);
;                 if (fq == 0) red[wc * 256 + (row & 255)] = ss;
.Lx_ok:
	s_lshl_b32 s9, s34, 8
	s_lshl_b32 s34, s8, 8
	v_add_u32_e32 v120, s9, v185
	s_ashr_i32 s35, s34, 31
	s_lshl_b64 s[36:37], s[34:35], 1
	v_ashrrev_i32_e32 v121, 31, v120
	v_or_b32_e32 v230, 16, v120
	v_lshl_add_u64 v[122:123], v[196:197], 0, s[36:37]
	v_lshlrev_b64 v[250:251], 11, v[120:121]
	v_ashrrev_i32_e32 v231, 31, v230
	v_or_b32_e32 v226, 32, v120
	v_lshl_add_u64 v[124:125], v[122:123], 0, v[250:251]
	v_lshlrev_b64 v[232:233], 11, v[230:231]
	v_ashrrev_i32_e32 v227, 31, v226
	v_or_b32_e32 v222, 48, v120
	global_load_dwordx4 v[242:245], v[124:125], off nt
	global_load_dwordx4 v[246:249], v[124:125], off offset:256 nt
	v_lshl_add_u64 v[124:125], v[122:123], 0, v[232:233]
	v_lshlrev_b64 v[228:229], 11, v[226:227]
	v_ashrrev_i32_e32 v223, 31, v222
	v_add_u32_e32 v218, 0x80, v120
	global_load_dwordx4 v[180:183], v[124:125], off nt
	global_load_dwordx4 v[176:179], v[124:125], off offset:256 nt
	v_lshl_add_u64 v[124:125], v[122:123], 0, v[228:229]
	v_lshlrev_b64 v[224:225], 11, v[222:223]
	v_ashrrev_i32_e32 v219, 31, v218
	v_add_u32_e32 v214, 0x90, v120
	global_load_dwordx4 v[172:175], v[124:125], off nt
	global_load_dwordx4 v[168:171], v[124:125], off offset:256 nt
	v_lshl_add_u64 v[124:125], v[122:123], 0, v[224:225]
	v_lshlrev_b64 v[220:221], 11, v[218:219]
	v_ashrrev_i32_e32 v215, 31, v214
	v_add_u32_e32 v210, 0xa0, v120
	v_add_u32_e32 v206, 0xb0, v120
	global_load_dwordx4 v[164:167], v[124:125], off nt
	global_load_dwordx4 v[160:163], v[124:125], off offset:256 nt
	v_lshl_add_u64 v[124:125], v[122:123], 0, v[220:221]
	v_lshlrev_b64 v[216:217], 11, v[214:215]
	v_ashrrev_i32_e32 v211, 31, v210
	v_ashrrev_i32_e32 v207, 31, v206
	global_load_dwordx4 v[156:159], v[124:125], off nt
	global_load_dwordx4 v[152:155], v[124:125], off offset:256 nt
	v_lshl_add_u64 v[124:125], v[122:123], 0, v[216:217]
	v_lshlrev_b64 v[212:213], 11, v[210:211]
	v_lshlrev_b64 v[208:209], 11, v[206:207]
	global_load_dwordx4 v[148:151], v[124:125], off nt
	global_load_dwordx4 v[144:147], v[124:125], off offset:256 nt
	v_lshl_add_u64 v[124:125], v[122:123], 0, v[212:213]
	v_lshl_add_u64 v[120:121], v[122:123], 0, v[208:209]
	global_load_dwordx4 v[140:143], v[124:125], off nt
	global_load_dwordx4 v[136:139], v[124:125], off offset:256 nt
	s_nop 0
	global_load_dwordx4 v[124:127], v[120:121], off nt
	s_nop 0
	global_load_dwordx4 v[120:123], v[120:121], off offset:256 nt
	s_waitcnt vmcnt(15)
	v_lshlrev_b32_e32 v207, 16, v242
	v_add_f32_e32 v207, v132, v207
	v_and_b32_e32 v132, 0xffff0000, v242
	v_add_f32_e32 v211, v133, v132
	v_lshlrev_b32_e32 v132, 16, v243
	v_add_f32_e32 v134, v134, v132
	v_and_b32_e32 v132, 0xffff0000, v243
	v_add_f32_e32 v135, v135, v132
	v_lshlrev_b32_e32 v132, 16, v244
	v_add_f32_e32 v215, v128, v132
	v_and_b32_e32 v128, 0xffff0000, v244
	v_add_f32_e32 v219, v129, v128
	v_lshlrev_b32_e32 v128, 16, v245
	v_add_f32_e32 v223, v130, v128
	v_and_b32_e32 v128, 0xffff0000, v245
	v_add_f32_e32 v131, v131, v128
	v_lshl_add_u64 v[128:129], s[16:17], 0, v[250:251]
	v_lshl_add_u64 v[128:129], v[128:129], 0, s[36:37]
	v_lshl_add_u64 v[128:129], v[128:129], 0, s[10:11]
	v_lshl_add_u64 v[132:133], v[128:129], 0, v[194:195]
	v_cvt_pk_bf16_f32 v128, v207, v211
	v_mul_f32_e32 v211, v211, v211
	v_fmac_f32_e32 v211, v207, v207
	v_fmac_f32_e32 v211, v134, v134
	v_fmac_f32_e32 v211, v135, v135
	v_fmac_f32_e32 v211, v215, v215
	s_waitcnt vmcnt(14)
	v_lshlrev_b32_e32 v130, 16, v246
	v_fmac_f32_e32 v211, v219, v219
	v_add_f32_e32 v116, v116, v130
	v_and_b32_e32 v130, 0xffff0000, v246
	v_fmac_f32_e32 v211, v223, v223
	v_add_f32_e32 v117, v117, v130
	v_lshlrev_b32_e32 v130, 16, v247
	v_fmac_f32_e32 v211, v131, v131
	v_add_f32_e32 v118, v118, v130
	v_and_b32_e32 v130, 0xffff0000, v247
	v_add_f32_e32 v119, v119, v130
	v_lshlrev_b32_e32 v130, 16, v248
	v_fmac_f32_e32 v211, v116, v116
	v_cvt_pk_bf16_f32 v129, v134, v135
	v_add_f32_e32 v134, v112, v130
	v_and_b32_e32 v112, 0xffff0000, v248
	v_fmac_f32_e32 v211, v117, v117
	v_add_f32_e32 v135, v113, v112
	v_lshlrev_b32_e32 v112, 16, v249
	v_fmac_f32_e32 v211, v118, v118
	v_add_f32_e32 v207, v114, v112
	v_and_b32_e32 v112, 0xffff0000, v249
	v_fmac_f32_e32 v211, v119, v119
	v_and_b32_e32 v113, 64, v240
	v_add_f32_e32 v227, v115, v112
	v_fmac_f32_e32 v211, v134, v134
	v_xor_b32_e32 v112, 16, v240
	v_add_u32_e32 v113, 64, v113
	v_fmac_f32_e32 v211, v135, v135
	v_cmp_lt_i32_e32 vcc, v112, v113
	v_fmac_f32_e32 v211, v207, v207
	v_fmac_f32_e32 v211, v227, v227
	v_cndmask_b32_e32 v112, v240, v112, vcc
	v_lshlrev_b32_e32 v112, 2, v112
	ds_bpermute_b32 v114, v112, v211
	v_xor_b32_e32 v115, 32, v240
	v_cmp_lt_i32_e32 vcc, v115, v113
	v_cvt_pk_bf16_f32 v130, v215, v219
	v_cvt_pk_bf16_f32 v131, v223, v131
	s_waitcnt lgkmcnt(0)
	v_add_f32_e32 v114, v211, v114
	global_store_dwordx4 v[132:133], v[128:131], off
	v_cndmask_b32_e32 v113, v240, v115, vcc
	v_lshlrev_b32_e32 v113, 2, v113
	ds_bpermute_b32 v115, v113, v114
	v_cvt_pk_bf16_f32 v116, v116, v117
	v_cvt_pk_bf16_f32 v117, v118, v119
	v_cvt_pk_bf16_f32 v118, v134, v135
	v_cvt_pk_bf16_f32 v119, v207, v227
	global_store_dwordx4 v[132:133], v[116:119], off offset:256
	s_and_saveexec_b64 s[36:37], s[2:3]
	s_cbranch_execz .LBB0_940
	s_waitcnt lgkmcnt(0)
	v_add_f32_e32 v114, v114, v115
	ds_write_b32 v235, v114
;     __device__ __forceinline__ void operator()(const f32x4 (&acc)[2][2][4][2], const pg8::Unit& u, int wr, int wc, int fr, int fq) const {
;     ...
;         for (int ai = 0; ai < 2; ++ai)
; #pragma unroll
;             for (int m = 0; m < 4; ++m) {
;                 const int row = u.pm * 256 + ai * 128 + wr * 64 + m * 16 + fr;
;                 float ss = 0.f;
; #pragma unroll
;                 for (int bj = 0; bj < 2; ++bj) {
;                     const size_t off = (size_t)row * DM + u.pn * 256 + 128 * bj + 32 * wc + 8 * fq;
;                     const u32x4 w = xr[ai][m][bj];
;                     float y[8];
;                     y[0] = __uint_as_float(w.x << 16) + acc[ai][bj][m][0].x; y[1] = __uint_as_float(w.x & 0xffff0000u) + acc[ai][bj][m][0].y;
;                     y[2] = __uint_as_float(w.y << 16) + acc[ai][bj][m][0].z; y[3] = __uint_as_float(w.y & 0xffff0000u) + acc[ai][bj][m][0].w;
;                     y[4] = __uint_as_float(w.z << 16) + acc[ai][bj][m][1].x; y[5] = __uint_as_float(w.z & 0xffff0000u) + acc[ai][bj][m][1].y;
;                     y[6] = __uint_as_float(w.w << 16) + acc[ai][bj][m][1].z; y[7] = __uint_as_float(w.w & 0xffff0000u) + acc[ai][bj][m][1].w;
;                     store8(x2b + off, y);
; #pragma unroll
;                     for (int i = 0; i < 8; ++i) ss += y[i] * y[i];
;                 }
;                 ss += __shfl_xor(ss, 16); ss += __shfl_xor(ss, 32);
;                 if (fq == 0) red[wc * 256 + (row & 255)] = ss;
.LBB0_940:
	s_or_b64 exec, exec, s[36:37]
	s_waitcnt vmcnt(13)
	v_lshlrev_b32_e32 v114, 16, v180
	v_add_f32_e32 v114, v108, v114
	v_and_b32_e32 v108, 0xffff0000, v180
	s_waitcnt lgkmcnt(0)
	v_add_f32_e32 v115, v109, v108
	v_lshlrev_b32_e32 v108, 16, v181
	v_add_f32_e32 v110, v110, v108
	v_and_b32_e32 v108, 0xffff0000, v181
	v_add_f32_e32 v111, v111, v108
	v_lshlrev_b32_e32 v108, 16, v182
	v_add_f32_e32 v116, v104, v108
	v_and_b32_e32 v104, 0xffff0000, v182
	v_add_f32_e32 v117, v105, v104
	v_lshlrev_b32_e32 v104, 16, v183
	v_add_f32_e32 v118, v106, v104
	v_and_b32_e32 v104, 0xffff0000, v183
	v_add_f32_e32 v107, v107, v104
	v_lshl_add_u64 v[104:105], s[16:17], 0, v[232:233]
	v_lshl_add_u64 v[104:105], s[34:35], 1, v[104:105]
	v_lshl_add_u64 v[104:105], v[104:105], 0, s[10:11]
	v_lshl_add_u64 v[108:109], v[104:105], 0, v[194:195]
	v_cvt_pk_bf16_f32 v104, v114, v115
	v_mul_f32_e32 v115, v115, v115
	v_fmac_f32_e32 v115, v114, v114
	v_fmac_f32_e32 v115, v110, v110
	v_fmac_f32_e32 v115, v111, v111
	v_fmac_f32_e32 v115, v116, v116
	v_fmac_f32_e32 v115, v117, v117
	v_fmac_f32_e32 v115, v118, v118
	s_waitcnt vmcnt(12)
	v_lshlrev_b32_e32 v106, 16, v176
	v_fmac_f32_e32 v115, v107, v107
	v_add_f32_e32 v100, v100, v106
	v_and_b32_e32 v106, 0xffff0000, v176
	v_add_f32_e32 v101, v101, v106
	v_lshlrev_b32_e32 v106, 16, v177
	v_fmac_f32_e32 v115, v100, v100
	v_add_f32_e32 v102, v102, v106
	v_and_b32_e32 v106, 0xffff0000, v177
	v_fmac_f32_e32 v115, v101, v101
	v_add_f32_e32 v103, v103, v106
	v_lshlrev_b32_e32 v106, 16, v178
	v_fmac_f32_e32 v115, v102, v102
	v_cvt_pk_bf16_f32 v105, v110, v111
	v_add_f32_e32 v110, v96, v106
	v_and_b32_e32 v96, 0xffff0000, v178
	v_fmac_f32_e32 v115, v103, v103
	v_add_f32_e32 v111, v97, v96
	v_lshlrev_b32_e32 v96, 16, v179
	v_fmac_f32_e32 v115, v110, v110
	v_add_f32_e32 v114, v98, v96
	v_and_b32_e32 v96, 0xffff0000, v179
	v_fmac_f32_e32 v115, v111, v111
	v_add_f32_e32 v119, v99, v96
	v_fmac_f32_e32 v115, v114, v114
	v_fmac_f32_e32 v115, v119, v119
	ds_bpermute_b32 v96, v112, v115
	v_cvt_pk_bf16_f32 v106, v116, v117
	v_cvt_pk_bf16_f32 v107, v118, v107
	global_store_dwordx4 v[108:109], v[104:107], off
	v_cvt_pk_bf16_f32 v98, v100, v101
	s_waitcnt lgkmcnt(0)
	v_add_f32_e32 v96, v115, v96
	ds_bpermute_b32 v97, v113, v96
	v_cvt_pk_bf16_f32 v99, v102, v103
	v_cvt_pk_bf16_f32 v100, v110, v111
	v_cvt_pk_bf16_f32 v101, v114, v119
	global_store_dwordx4 v[108:109], v[98:101], off offset:256
	s_and_saveexec_b64 s[36:37], s[2:3]
	s_cbranch_execz .LBB0_942
	v_and_b32_e32 v98, 0xdf, v230
	v_lshl_add_u32 v98, v98, 2, s52
	s_waitcnt lgkmcnt(0)
	v_add_f32_e32 v96, v96, v97
	ds_write_b32 v98, v96
.LBB0_942:
	s_or_b64 exec, exec, s[36:37]
	s_waitcnt vmcnt(11)
	v_lshlrev_b32_e32 v96, 16, v172
	v_add_f32_e32 v96, v92, v96
	v_and_b32_e32 v92, 0xffff0000, v172
	s_waitcnt lgkmcnt(0)
	v_add_f32_e32 v97, v93, v92
	v_lshlrev_b32_e32 v92, 16, v173
	v_add_f32_e32 v94, v94, v92
	v_and_b32_e32 v92, 0xffff0000, v173
	v_add_f32_e32 v95, v95, v92
	v_lshlrev_b32_e32 v92, 16, v174
	v_add_f32_e32 v98, v88, v92
	v_and_b32_e32 v88, 0xffff0000, v174
	v_add_f32_e32 v99, v89, v88
	v_lshlrev_b32_e32 v88, 16, v175
	v_add_f32_e32 v100, v90, v88
	v_and_b32_e32 v88, 0xffff0000, v175
	v_add_f32_e32 v91, v91, v88
	v_lshl_add_u64 v[88:89], s[16:17], 0, v[228:229]
	v_lshl_add_u64 v[88:89], s[34:35], 1, v[88:89]
	v_lshl_add_u64 v[88:89], v[88:89], 0, s[10:11]
	v_lshl_add_u64 v[92:93], v[88:89], 0, v[194:195]
	v_cvt_pk_bf16_f32 v88, v96, v97
	v_mul_f32_e32 v97, v97, v97
	v_fmac_f32_e32 v97, v96, v96
	v_fmac_f32_e32 v97, v94, v94
	v_fmac_f32_e32 v97, v95, v95
	v_fmac_f32_e32 v97, v98, v98
	v_fmac_f32_e32 v97, v99, v99
	v_fmac_f32_e32 v97, v100, v100
	s_waitcnt vmcnt(10)
	v_lshlrev_b32_e32 v90, 16, v168
	v_fmac_f32_e32 v97, v91, v91
	v_add_f32_e32 v84, v84, v90
	v_and_b32_e32 v90, 0xffff0000, v168
	v_add_f32_e32 v85, v85, v90
	v_lshlrev_b32_e32 v90, 16, v169
	v_fmac_f32_e32 v97, v84, v84
	v_add_f32_e32 v86, v86, v90
	v_and_b32_e32 v90, 0xffff0000, v169
	v_fmac_f32_e32 v97, v85, v85
	v_add_f32_e32 v87, v87, v90
	v_lshlrev_b32_e32 v90, 16, v170
	v_fmac_f32_e32 v97, v86, v86
	v_cvt_pk_bf16_f32 v89, v94, v95
	v_add_f32_e32 v94, v80, v90
	v_and_b32_e32 v80, 0xffff0000, v170
	v_fmac_f32_e32 v97, v87, v87
	v_add_f32_e32 v95, v81, v80
	v_lshlrev_b32_e32 v80, 16, v171
	v_fmac_f32_e32 v97, v94, v94
	v_add_f32_e32 v96, v82, v80
	v_and_b32_e32 v80, 0xffff0000, v171
	v_fmac_f32_e32 v97, v95, v95
	v_add_f32_e32 v101, v83, v80
	v_fmac_f32_e32 v97, v96, v96
	v_fmac_f32_e32 v97, v101, v101
	ds_bpermute_b32 v80, v112, v97
	v_cvt_pk_bf16_f32 v90, v98, v99
	v_cvt_pk_bf16_f32 v91, v100, v91
	global_store_dwordx4 v[92:93], v[88:91], off
	v_cvt_pk_bf16_f32 v82, v84, v85
	s_waitcnt lgkmcnt(0)
	v_add_f32_e32 v80, v97, v80
	ds_bpermute_b32 v81, v113, v80
	v_cvt_pk_bf16_f32 v83, v86, v87
	v_cvt_pk_bf16_f32 v84, v94, v95
	v_cvt_pk_bf16_f32 v85, v96, v101
	global_store_dwordx4 v[92:93], v[82:85], off offset:256
	s_and_saveexec_b64 s[36:37], s[2:3]
	s_cbranch_execz .LBB0_944
	v_and_b32_e32 v82, 0xef, v226
	v_lshl_add_u32 v82, v82, 2, s52
	s_waitcnt lgkmcnt(0)
	v_add_f32_e32 v80, v80, v81
	ds_write_b32 v82, v80
;     __device__ __forceinline__ void operator()(const f32x4 (&acc)[2][2][4][2], const pg8::Unit& u, int wr, int wc, int fr, int fq) const {
;     ...
;         for (int ai = 0; ai < 2; ++ai)
; #pragma unroll
;             for (int m = 0; m < 4; ++m) {
;                 const int row = u.pm * 256 + ai * 128 + wr * 64 + m * 16 + fr;
;                 float ss = 0.f;
; #pragma unroll
;                 for (int bj = 0; bj < 2; ++bj) {
;                     const size_t off = (size_t)row * DM + u.pn * 256 + 128 * bj + 32 * wc + 8 * fq;
;                     const u32x4 w = xr[ai][m][bj];
;                     float y[8];
;                     y[0] = __uint_as_float(w.x << 16) + acc[ai][bj][m][0].x; y[1] = __uint_as_float(w.x & 0xffff0000u) + acc[ai][bj][m][0].y;
;                     y[2] = __uint_as_float(w.y << 16) + acc[ai][bj][m][0].z; y[3] = __uint_as_float(w.y & 0xffff0000u) + acc[ai][bj][m][0].w;
;                     y[4] = __uint_as_float(w.z << 16) + acc[ai][bj][m][1].x; y[5] = __uint_as_float(w.z & 0xffff0000u) + acc[ai][bj][m][1].y;
;                     y[6] = __uint_as_float(w.w << 16) + acc[ai][bj][m][1].z; y[7] = __uint_as_float(w.w & 0xffff0000u) + acc[ai][bj][m][1].w;
;                     store8(x2b + off, y);
; #pragma unroll
;                     for (int i = 0; i < 8; ++i) ss += y[i] * y[i];
;                 }
;                 ss += __shfl_xor(ss, 16); ss += __shfl_xor(ss, 32);
;                 if (fq == 0) red[wc * 256 + (row & 255)] = ss;
.LBB0_944:
	s_or_b64 exec, exec, s[36:37]
	s_waitcnt vmcnt(9)
	v_lshlrev_b32_e32 v80, 16, v164
	v_add_f32_e32 v80, v76, v80
	v_and_b32_e32 v76, 0xffff0000, v164
	s_waitcnt lgkmcnt(0)
	v_add_f32_e32 v81, v77, v76
	v_lshlrev_b32_e32 v76, 16, v165
	v_add_f32_e32 v78, v78, v76
	v_and_b32_e32 v76, 0xffff0000, v165
	v_add_f32_e32 v79, v79, v76
	v_lshlrev_b32_e32 v76, 16, v166
	v_add_f32_e32 v82, v72, v76
	v_and_b32_e32 v72, 0xffff0000, v166
	v_add_f32_e32 v83, v73, v72
	v_lshlrev_b32_e32 v72, 16, v167
	v_add_f32_e32 v84, v74, v72
	v_and_b32_e32 v72, 0xffff0000, v167
	v_add_f32_e32 v75, v75, v72
	v_lshl_add_u64 v[72:73], s[16:17], 0, v[224:225]
	v_lshl_add_u64 v[72:73], s[34:35], 1, v[72:73]
	v_lshl_add_u64 v[72:73], v[72:73], 0, s[10:11]
	v_lshl_add_u64 v[76:77], v[72:73], 0, v[194:195]
	v_cvt_pk_bf16_f32 v72, v80, v81
	v_mul_f32_e32 v81, v81, v81
	v_fmac_f32_e32 v81, v80, v80
	v_fmac_f32_e32 v81, v78, v78
	v_fmac_f32_e32 v81, v79, v79
	v_fmac_f32_e32 v81, v82, v82
	v_fmac_f32_e32 v81, v83, v83
	v_fmac_f32_e32 v81, v84, v84
	s_waitcnt vmcnt(8)
	v_lshlrev_b32_e32 v74, 16, v160
	v_fmac_f32_e32 v81, v75, v75
	v_add_f32_e32 v68, v68, v74
	v_and_b32_e32 v74, 0xffff0000, v160
	v_add_f32_e32 v69, v69, v74
	v_lshlrev_b32_e32 v74, 16, v161
	v_fmac_f32_e32 v81, v68, v68
	v_add_f32_e32 v70, v70, v74
	v_and_b32_e32 v74, 0xffff0000, v161
	v_fmac_f32_e32 v81, v69, v69
	v_add_f32_e32 v71, v71, v74
	v_lshlrev_b32_e32 v74, 16, v162
	v_fmac_f32_e32 v81, v70, v70
	v_cvt_pk_bf16_f32 v73, v78, v79
	v_add_f32_e32 v78, v64, v74
	v_and_b32_e32 v64, 0xffff0000, v162
	v_fmac_f32_e32 v81, v71, v71
	v_add_f32_e32 v79, v65, v64
	v_lshlrev_b32_e32 v64, 16, v163
	v_fmac_f32_e32 v81, v78, v78
	v_add_f32_e32 v80, v66, v64
	v_and_b32_e32 v64, 0xffff0000, v163
	v_fmac_f32_e32 v81, v79, v79
	v_add_f32_e32 v85, v67, v64
	v_fmac_f32_e32 v81, v80, v80
	v_fmac_f32_e32 v81, v85, v85
	ds_bpermute_b32 v64, v112, v81
	v_cvt_pk_bf16_f32 v74, v82, v83
	v_cvt_pk_bf16_f32 v75, v84, v75
	global_store_dwordx4 v[76:77], v[72:75], off
	v_cvt_pk_bf16_f32 v66, v68, v69
	s_waitcnt lgkmcnt(0)
	v_add_f32_e32 v64, v81, v64
	ds_bpermute_b32 v65, v113, v64
	v_cvt_pk_bf16_f32 v67, v70, v71
	v_cvt_pk_bf16_f32 v68, v78, v79
	v_cvt_pk_bf16_f32 v69, v80, v85
	global_store_dwordx4 v[76:77], v[66:69], off offset:256
	s_and_saveexec_b64 s[36:37], s[2:3]
	s_cbranch_execz .LBB0_946
	v_and_b32_e32 v66, 0xff, v222
	v_lshl_add_u32 v66, v66, 2, s52
	s_waitcnt lgkmcnt(0)
	v_add_f32_e32 v64, v64, v65
	ds_write_b32 v66, v64
.LBB0_946:
	s_or_b64 exec, exec, s[36:37]
	s_waitcnt vmcnt(7)
	v_lshlrev_b32_e32 v64, 16, v156
	v_add_f32_e32 v64, v60, v64
	v_and_b32_e32 v60, 0xffff0000, v156
	s_waitcnt lgkmcnt(0)
	v_add_f32_e32 v65, v61, v60
	v_lshlrev_b32_e32 v60, 16, v157
	v_add_f32_e32 v62, v62, v60
	v_and_b32_e32 v60, 0xffff0000, v157
	v_add_f32_e32 v63, v63, v60
	v_lshlrev_b32_e32 v60, 16, v158
	v_add_f32_e32 v66, v56, v60
	v_and_b32_e32 v56, 0xffff0000, v158
	v_add_f32_e32 v67, v57, v56
	v_lshlrev_b32_e32 v56, 16, v159
	v_add_f32_e32 v68, v58, v56
	v_and_b32_e32 v56, 0xffff0000, v159
	v_add_f32_e32 v59, v59, v56
	v_lshl_add_u64 v[56:57], s[16:17], 0, v[220:221]
	v_lshl_add_u64 v[56:57], s[34:35], 1, v[56:57]
	v_lshl_add_u64 v[56:57], v[56:57], 0, s[10:11]
	v_lshl_add_u64 v[60:61], v[56:57], 0, v[194:195]
	v_cvt_pk_bf16_f32 v56, v64, v65
	v_mul_f32_e32 v65, v65, v65
	v_fmac_f32_e32 v65, v64, v64
	v_fmac_f32_e32 v65, v62, v62
	v_fmac_f32_e32 v65, v63, v63
	v_fmac_f32_e32 v65, v66, v66
	v_fmac_f32_e32 v65, v67, v67
	v_fmac_f32_e32 v65, v68, v68
	s_waitcnt vmcnt(6)
	v_lshlrev_b32_e32 v58, 16, v152
	v_fmac_f32_e32 v65, v59, v59
	v_add_f32_e32 v52, v52, v58
	v_and_b32_e32 v58, 0xffff0000, v152
	v_add_f32_e32 v53, v53, v58
	v_lshlrev_b32_e32 v58, 16, v153
	v_fmac_f32_e32 v65, v52, v52
	v_add_f32_e32 v54, v54, v58
	v_and_b32_e32 v58, 0xffff0000, v153
	v_fmac_f32_e32 v65, v53, v53
	v_add_f32_e32 v55, v55, v58
	v_lshlrev_b32_e32 v58, 16, v154
	v_fmac_f32_e32 v65, v54, v54
	v_cvt_pk_bf16_f32 v57, v62, v63
	v_add_f32_e32 v62, v48, v58
	v_and_b32_e32 v48, 0xffff0000, v154
	v_fmac_f32_e32 v65, v55, v55
	v_add_f32_e32 v63, v49, v48
	v_lshlrev_b32_e32 v48, 16, v155
	v_fmac_f32_e32 v65, v62, v62
	v_add_f32_e32 v64, v50, v48
	v_and_b32_e32 v48, 0xffff0000, v155
	v_fmac_f32_e32 v65, v63, v63
	v_add_f32_e32 v69, v51, v48
	v_fmac_f32_e32 v65, v64, v64
	v_fmac_f32_e32 v65, v69, v69
	ds_bpermute_b32 v48, v112, v65
	v_cvt_pk_bf16_f32 v58, v66, v67
	v_cvt_pk_bf16_f32 v59, v68, v59
	global_store_dwordx4 v[60:61], v[56:59], off
	v_cvt_pk_bf16_f32 v50, v52, v53
	s_waitcnt lgkmcnt(0)
	v_add_f32_e32 v48, v65, v48
	ds_bpermute_b32 v49, v113, v48
	v_cvt_pk_bf16_f32 v51, v54, v55
	v_cvt_pk_bf16_f32 v52, v62, v63
	v_cvt_pk_bf16_f32 v53, v64, v69
	global_store_dwordx4 v[60:61], v[50:53], off offset:256
	s_and_saveexec_b64 s[36:37], s[2:3]
	s_cbranch_execz .LBB0_948
	v_and_b32_e32 v50, 0xcf, v218
	v_lshl_add_u32 v50, v50, 2, s52
	s_waitcnt lgkmcnt(0)
	v_add_f32_e32 v48, v48, v49
	ds_write_b32 v50, v48
;     __device__ __forceinline__ void operator()(const f32x4 (&acc)[2][2][4][2], const pg8::Unit& u, int wr, int wc, int fr, int fq) const {
;     ...
;         for (int ai = 0; ai < 2; ++ai)
; #pragma unroll
;             for (int m = 0; m < 4; ++m) {
;                 const int row = u.pm * 256 + ai * 128 + wr * 64 + m * 16 + fr;
;                 float ss = 0.f;
; #pragma unroll
;                 for (int bj = 0; bj < 2; ++bj) {
;                     const size_t off = (size_t)row * DM + u.pn * 256 + 128 * bj + 32 * wc + 8 * fq;
;                     const u32x4 w = xr[ai][m][bj];
;                     float y[8];
;                     y[0] = __uint_as_float(w.x << 16) + acc[ai][bj][m][0].x; y[1] = __uint_as_float(w.x & 0xffff0000u) + acc[ai][bj][m][0].y;
;                     y[2] = __uint_as_float(w.y << 16) + acc[ai][bj][m][0].z; y[3] = __uint_as_float(w.y & 0xffff0000u) + acc[ai][bj][m][0].w;
;                     y[4] = __uint_as_float(w.z << 16) + acc[ai][bj][m][1].x; y[5] = __uint_as_float(w.z & 0xffff0000u) + acc[ai][bj][m][1].y;
;                     y[6] = __uint_as_float(w.w << 16) + acc[ai][bj][m][1].z; y[7] = __uint_as_float(w.w & 0xffff0000u) + acc[ai][bj][m][1].w;
;                     store8(x2b + off, y);
; #pragma unroll
;                     for (int i = 0; i < 8; ++i) ss += y[i] * y[i];
;                 }
;                 ss += __shfl_xor(ss, 16); ss += __shfl_xor(ss, 32);
;                 if (fq == 0) red[wc * 256 + (row & 255)] = ss;
.LBB0_948:
	s_or_b64 exec, exec, s[36:37]
	s_waitcnt vmcnt(5)
	v_lshlrev_b32_e32 v48, 16, v148
	v_add_f32_e32 v48, v44, v48
	v_and_b32_e32 v44, 0xffff0000, v148
	s_waitcnt lgkmcnt(0)
	v_add_f32_e32 v49, v45, v44
	v_lshlrev_b32_e32 v44, 16, v149
	v_add_f32_e32 v46, v46, v44
	v_and_b32_e32 v44, 0xffff0000, v149
	v_add_f32_e32 v47, v47, v44
	v_lshlrev_b32_e32 v44, 16, v150
	v_add_f32_e32 v50, v40, v44
	v_and_b32_e32 v40, 0xffff0000, v150
	v_add_f32_e32 v51, v41, v40
	v_lshlrev_b32_e32 v40, 16, v151
	v_add_f32_e32 v52, v42, v40
	v_and_b32_e32 v40, 0xffff0000, v151
	v_add_f32_e32 v43, v43, v40
	v_lshl_add_u64 v[40:41], s[16:17], 0, v[216:217]
	v_lshl_add_u64 v[40:41], s[34:35], 1, v[40:41]
	v_lshl_add_u64 v[40:41], v[40:41], 0, s[10:11]
	v_lshl_add_u64 v[44:45], v[40:41], 0, v[194:195]
	v_cvt_pk_bf16_f32 v40, v48, v49
	v_mul_f32_e32 v49, v49, v49
	v_fmac_f32_e32 v49, v48, v48
	v_fmac_f32_e32 v49, v46, v46
	v_fmac_f32_e32 v49, v47, v47
	v_fmac_f32_e32 v49, v50, v50
	v_fmac_f32_e32 v49, v51, v51
	v_fmac_f32_e32 v49, v52, v52
	s_waitcnt vmcnt(4)
	v_lshlrev_b32_e32 v42, 16, v144
	v_fmac_f32_e32 v49, v43, v43
	v_add_f32_e32 v36, v36, v42
	v_and_b32_e32 v42, 0xffff0000, v144
	v_add_f32_e32 v37, v37, v42
	v_lshlrev_b32_e32 v42, 16, v145
	v_fmac_f32_e32 v49, v36, v36
	v_add_f32_e32 v38, v38, v42
	v_and_b32_e32 v42, 0xffff0000, v145
	v_fmac_f32_e32 v49, v37, v37
	v_add_f32_e32 v39, v39, v42
	v_lshlrev_b32_e32 v42, 16, v146
	v_fmac_f32_e32 v49, v38, v38
	v_cvt_pk_bf16_f32 v41, v46, v47
	v_add_f32_e32 v46, v32, v42
	v_and_b32_e32 v32, 0xffff0000, v146
	v_fmac_f32_e32 v49, v39, v39
	v_add_f32_e32 v47, v33, v32
	v_lshlrev_b32_e32 v32, 16, v147
	v_fmac_f32_e32 v49, v46, v46
	v_add_f32_e32 v48, v34, v32
	v_and_b32_e32 v32, 0xffff0000, v147
	v_fmac_f32_e32 v49, v47, v47
	v_add_f32_e32 v53, v35, v32
	v_fmac_f32_e32 v49, v48, v48
	v_fmac_f32_e32 v49, v53, v53
	ds_bpermute_b32 v32, v112, v49
	v_cvt_pk_bf16_f32 v42, v50, v51
	v_cvt_pk_bf16_f32 v43, v52, v43
	global_store_dwordx4 v[44:45], v[40:43], off
	v_cvt_pk_bf16_f32 v34, v36, v37
	s_waitcnt lgkmcnt(0)
	v_add_f32_e32 v32, v49, v32
	ds_bpermute_b32 v33, v113, v32
	v_cvt_pk_bf16_f32 v35, v38, v39
	v_cvt_pk_bf16_f32 v36, v46, v47
	v_cvt_pk_bf16_f32 v37, v48, v53
	global_store_dwordx4 v[44:45], v[34:37], off offset:256
	s_and_saveexec_b64 s[36:37], s[2:3]
	s_cbranch_execz .LBB0_950
	v_and_b32_e32 v34, 0xdf, v214
	v_lshl_add_u32 v34, v34, 2, s52
	s_waitcnt lgkmcnt(0)
	v_add_f32_e32 v32, v32, v33
	ds_write_b32 v34, v32
;     __device__ __forceinline__ void operator()(const f32x4 (&acc)[2][2][4][2], const pg8::Unit& u, int wr, int wc, int fr, int fq) const {
;     ...
;         for (int ai = 0; ai < 2; ++ai)
; #pragma unroll
;             for (int m = 0; m < 4; ++m) {
;                 const int row = u.pm * 256 + ai * 128 + wr * 64 + m * 16 + fr;
;                 float ss = 0.f;
; #pragma unroll
;                 for (int bj = 0; bj < 2; ++bj) {
;                     const size_t off = (size_t)row * DM + u.pn * 256 + 128 * bj + 32 * wc + 8 * fq;
;                     const u32x4 w = xr[ai][m][bj];
;                     float y[8];
;                     y[0] = __uint_as_float(w.x << 16) + acc[ai][bj][m][0].x; y[1] = __uint_as_float(w.x & 0xffff0000u) + acc[ai][bj][m][0].y;
;                     y[2] = __uint_as_float(w.y << 16) + acc[ai][bj][m][0].z; y[3] = __uint_as_float(w.y & 0xffff0000u) + acc[ai][bj][m][0].w;
;                     y[4] = __uint_as_float(w.z << 16) + acc[ai][bj][m][1].x; y[5] = __uint_as_float(w.z & 0xffff0000u) + acc[ai][bj][m][1].y;
;                     y[6] = __uint_as_float(w.w << 16) + acc[ai][bj][m][1].z; y[7] = __uint_as_float(w.w & 0xffff0000u) + acc[ai][bj][m][1].w;
;                     store8(x2b + off, y);
; #pragma unroll
;                     for (int i = 0; i < 8; ++i) ss += y[i] * y[i];
;                 }
;                 ss += __shfl_xor(ss, 16); ss += __shfl_xor(ss, 32);
;                 if (fq == 0) red[wc * 256 + (row & 255)] = ss;
.LBB0_950:
	s_or_b64 exec, exec, s[36:37]
	s_waitcnt vmcnt(3)
	v_lshlrev_b32_e32 v32, 16, v140
	v_add_f32_e32 v32, v28, v32
	v_and_b32_e32 v28, 0xffff0000, v140
	s_waitcnt lgkmcnt(0)
	v_add_f32_e32 v33, v29, v28
	v_lshlrev_b32_e32 v28, 16, v141
	v_add_f32_e32 v30, v30, v28
	v_and_b32_e32 v28, 0xffff0000, v141
	v_add_f32_e32 v31, v31, v28
	v_lshlrev_b32_e32 v28, 16, v142
	v_add_f32_e32 v34, v24, v28
	v_and_b32_e32 v24, 0xffff0000, v142
	v_add_f32_e32 v35, v25, v24
	v_lshlrev_b32_e32 v24, 16, v143
	v_add_f32_e32 v36, v26, v24
	v_and_b32_e32 v24, 0xffff0000, v143
	v_add_f32_e32 v27, v27, v24
	v_lshl_add_u64 v[24:25], s[16:17], 0, v[212:213]
	v_lshl_add_u64 v[24:25], s[34:35], 1, v[24:25]
	v_lshl_add_u64 v[24:25], v[24:25], 0, s[10:11]
	v_lshl_add_u64 v[28:29], v[24:25], 0, v[194:195]
	v_cvt_pk_bf16_f32 v24, v32, v33
	v_mul_f32_e32 v33, v33, v33
	v_fmac_f32_e32 v33, v32, v32
	v_fmac_f32_e32 v33, v30, v30
	v_fmac_f32_e32 v33, v31, v31
	v_fmac_f32_e32 v33, v34, v34
	v_fmac_f32_e32 v33, v35, v35
	v_fmac_f32_e32 v33, v36, v36
	s_waitcnt vmcnt(2)
	v_lshlrev_b32_e32 v26, 16, v136
	v_fmac_f32_e32 v33, v27, v27
	v_add_f32_e32 v20, v20, v26
	v_and_b32_e32 v26, 0xffff0000, v136
	v_add_f32_e32 v21, v21, v26
	v_lshlrev_b32_e32 v26, 16, v137
	v_fmac_f32_e32 v33, v20, v20
	v_add_f32_e32 v22, v22, v26
	v_and_b32_e32 v26, 0xffff0000, v137
	v_fmac_f32_e32 v33, v21, v21
	v_add_f32_e32 v23, v23, v26
	v_lshlrev_b32_e32 v26, 16, v138
	v_fmac_f32_e32 v33, v22, v22
	v_cvt_pk_bf16_f32 v25, v30, v31
	v_add_f32_e32 v30, v16, v26
	v_and_b32_e32 v16, 0xffff0000, v138
	v_fmac_f32_e32 v33, v23, v23
	v_add_f32_e32 v31, v17, v16
	v_lshlrev_b32_e32 v16, 16, v139
	v_fmac_f32_e32 v33, v30, v30
	v_add_f32_e32 v32, v18, v16
	v_and_b32_e32 v16, 0xffff0000, v139
	v_fmac_f32_e32 v33, v31, v31
	v_add_f32_e32 v37, v19, v16
	v_fmac_f32_e32 v33, v32, v32
	v_fmac_f32_e32 v33, v37, v37
	ds_bpermute_b32 v16, v112, v33
	v_cvt_pk_bf16_f32 v26, v34, v35
	v_cvt_pk_bf16_f32 v27, v36, v27
	global_store_dwordx4 v[28:29], v[24:27], off
	v_cvt_pk_bf16_f32 v18, v20, v21
	s_waitcnt lgkmcnt(0)
	v_add_f32_e32 v16, v33, v16
	ds_bpermute_b32 v17, v113, v16
	v_cvt_pk_bf16_f32 v19, v22, v23
	v_cvt_pk_bf16_f32 v20, v30, v31
	v_cvt_pk_bf16_f32 v21, v32, v37
	global_store_dwordx4 v[28:29], v[18:21], off offset:256
	s_and_saveexec_b64 s[36:37], s[2:3]
	s_cbranch_execz .LBB0_952
	v_and_b32_e32 v18, 0xef, v210
	v_lshl_add_u32 v18, v18, 2, s52
	s_waitcnt lgkmcnt(0)
	v_add_f32_e32 v16, v16, v17
	ds_write_b32 v18, v16
.LBB0_952:
	s_or_b64 exec, exec, s[36:37]
	s_waitcnt vmcnt(1)
	v_lshlrev_b32_e32 v16, 16, v124
	v_add_f32_e32 v16, v12, v16
	v_and_b32_e32 v12, 0xffff0000, v124
	s_waitcnt lgkmcnt(0)
	v_add_f32_e32 v17, v13, v12
	v_lshlrev_b32_e32 v12, 16, v125
	v_add_f32_e32 v14, v14, v12
	v_and_b32_e32 v12, 0xffff0000, v125
	v_add_f32_e32 v15, v15, v12
	v_lshlrev_b32_e32 v12, 16, v126
	v_add_f32_e32 v18, v8, v12
	v_and_b32_e32 v8, 0xffff0000, v126
	v_add_f32_e32 v19, v9, v8
	v_lshlrev_b32_e32 v8, 16, v127
	v_add_f32_e32 v20, v10, v8
	v_and_b32_e32 v8, 0xffff0000, v127
	v_add_f32_e32 v11, v11, v8
	v_lshl_add_u64 v[8:9], s[16:17], 0, v[208:209]
	v_lshl_add_u64 v[8:9], s[34:35], 1, v[8:9]
	v_lshl_add_u64 v[8:9], v[8:9], 0, s[10:11]
	v_lshl_add_u64 v[12:13], v[8:9], 0, v[194:195]
	v_cvt_pk_bf16_f32 v8, v16, v17
	v_mul_f32_e32 v17, v17, v17
	v_fmac_f32_e32 v17, v16, v16
	v_fmac_f32_e32 v17, v14, v14
	v_fmac_f32_e32 v17, v15, v15
	v_fmac_f32_e32 v17, v18, v18
	v_fmac_f32_e32 v17, v19, v19
	v_fmac_f32_e32 v17, v20, v20
	s_waitcnt vmcnt(0)
	v_lshlrev_b32_e32 v10, 16, v120
	v_fmac_f32_e32 v17, v11, v11
	v_add_f32_e32 v4, v4, v10
	v_and_b32_e32 v10, 0xffff0000, v120
	v_add_f32_e32 v5, v5, v10
	v_lshlrev_b32_e32 v10, 16, v121
	v_fmac_f32_e32 v17, v4, v4
	v_add_f32_e32 v6, v6, v10
	v_and_b32_e32 v10, 0xffff0000, v121
	v_fmac_f32_e32 v17, v5, v5
	v_add_f32_e32 v7, v7, v10
	v_lshlrev_b32_e32 v10, 16, v122
	v_fmac_f32_e32 v17, v6, v6
	v_cvt_pk_bf16_f32 v9, v14, v15
	v_add_f32_e32 v14, v0, v10
	v_and_b32_e32 v0, 0xffff0000, v122
	v_fmac_f32_e32 v17, v7, v7
	v_add_f32_e32 v15, v1, v0
	v_lshlrev_b32_e32 v0, 16, v123
	v_fmac_f32_e32 v17, v14, v14
	v_add_f32_e32 v16, v2, v0
	v_and_b32_e32 v0, 0xffff0000, v123
	v_fmac_f32_e32 v17, v15, v15
	v_add_f32_e32 v21, v3, v0
	v_fmac_f32_e32 v17, v16, v16
	v_fmac_f32_e32 v17, v21, v21
	ds_bpermute_b32 v0, v112, v17
	v_cvt_pk_bf16_f32 v10, v18, v19
	v_cvt_pk_bf16_f32 v11, v20, v11
	global_store_dwordx4 v[12:13], v[8:11], off
	v_cvt_pk_bf16_f32 v2, v4, v5
	s_waitcnt lgkmcnt(0)
	v_add_f32_e32 v0, v17, v0
	ds_bpermute_b32 v1, v113, v0
	v_cvt_pk_bf16_f32 v3, v6, v7
	v_cvt_pk_bf16_f32 v4, v14, v15
	v_cvt_pk_bf16_f32 v5, v16, v21
	global_store_dwordx4 v[12:13], v[2:5], off offset:256
	s_and_saveexec_b64 s[34:35], s[2:3]
	s_cbranch_execz .LBB0_954
	v_and_b32_e32 v2, 0xff, v206
	v_lshl_add_u32 v2, v2, 2, s52
	s_waitcnt lgkmcnt(0)
	v_add_f32_e32 v0, v0, v1
	ds_write_b32 v2, v0
